# static-prio1-waves4-7-no-toggles
# baseline (speedup 1.0000x reference)
; #define LAS __attribute__((address_space(3)))
; __device__ __forceinline__ unsigned xb_add(unsigned* p, unsigned v) { return __hip_atomic_fetch_add(p, v, __ATOMIC_RELAXED, __HIP_MEMORY_SCOPE_AGENT); }
; __device__ __forceinline__ unsigned xb_xcc_id() { return (unsigned)__builtin_amdgcn_s_getreg((3 << 11) | 20) & 0xFu; }
; __device__ __forceinline__ KArgs kargs() { KArgs p = (KArgs)__builtin_amdgcn_kernarg_segment_ptr(); asm volatile("" : "+s"(p)); return p; }
; __device__ __forceinline__ XcdBarrier xcd_barrier_post(unsigned* bar, volatile LAS unsigned* st) {
;     XcdBarrier b; b.bar = bar; b.x = xb_xcc_id(); b.st = st;
;     if (threadIdx.x == 0) (void)xb_add(&bar[XB_XCNT(b.x)], 1u);
;     return b;
; __global__ void __launch_bounds__(512, 2) fwd_megakernel(Args a_kernarg) {
;     extern __shared__ __attribute__((aligned(16))) unsigned char lds_raw[];
;     cg::grid_group grid = cg::this_grid();
;     ...
;     { volatile LAS unsigned* st0 = (volatile LAS unsigned*)((LAS unsigned char*)lds_raw + LDS_BYTES - 64); if (threadIdx.x < 2) st0[threadIdx.x] = 0u; }
;     __syncthreads();
;     const XcdBarrier xbar = xcd_barrier_post((unsigned*)(kargs()->ws), (volatile LAS unsigned*)((LAS unsigned char*)lds_raw + LDS_BYTES - 64));
_Z14fwd_megakernel4Args:
	s_mov_b64 s[86:87], s[0:1]
	s_load_dwordx2 s[84:85], s[0:1], 0xa8
	s_nop 0
	s_load_dword s0, s[0:1], 0xb0
	v_and_b32_e32 v186, 0x3ff, v0
	s_mov_b32 s82, s2
	v_cmp_gt_u32_e32 vcc, 2, v186
	s_waitcnt lgkmcnt(0)
	v_writelane_b32 v254, s0, 0
	s_add_u32 s0, s86, 0xa8
	s_addc_u32 s1, s87, 0
	s_and_saveexec_b64 s[2:3], vcc
	v_lshl_add_u32 v1, v186, 2, 0
	v_add_u32_e32 v1, 0x23fc0, v1
	v_mov_b32_e32 v2, 0
	ds_write_b32 v1, v2
	s_or_b64 exec, exec, s[2:3]
	v_readfirstlane_b32 s98, v186
	s_cmpk_lt_u32 s98, 0x100
	s_cbranch_scc1 .Lprio_lo
	s_setprio 1
.Lprio_lo:
	s_mov_b64 s[2:3], s[86:87]
	s_waitcnt lgkmcnt(0)
	s_barrier
	s_load_dwordx2 s[20:21], s[2:3], 0xa0
	s_getreg_b32 s2, hwreg(HW_REG_XCC_ID, 0, 4)
	s_and_b32 s2, s2, 15
	v_writelane_b32 v254, s2, 1
	v_cmp_eq_u32_e64 s[4:5], 0, v186
	s_mov_b64 s[2:3], exec
	s_nop 0
	v_writelane_b32 v254, s4, 2
	s_nop 1
	v_writelane_b32 v254, s5, 3
	s_and_b64 s[4:5], s[2:3], s[4:5]
	s_mov_b64 exec, s[4:5]
	s_cbranch_execz .LBB0_5
	s_mov_b64 s[4:5], exec
	v_mbcnt_lo_u32_b32 v1, s4, 0
	v_mbcnt_hi_u32_b32 v1, s5, v1
	v_cmp_eq_u32_e32 vcc, 0, v1
	s_and_b64 s[6:7], exec, vcc
	s_mov_b64 exec, s[6:7]
	s_cbranch_execz .LBB0_5
	v_readlane_b32 s6, v254, 1
	s_lshl_b32 s6, s6, 8
	s_bcnt1_i32_b64 s4, s[4:5]
	v_mov_b32_e32 v1, s6
	v_mov_b32_e32 v2, s4
	s_waitcnt lgkmcnt(0)
	global_atomic_add v1, v2, s[20:21] offset:1024
